# FFN-down sample tiles K-split 8 ways over 128 blocks (partials in dead Z region), wt tiles re-dealt
# baseline (speedup 1.0000x reference)
.LBB0_62:
	s_or_b64 exec, exec, s[0:1]
	v_ashrrev_i32_e32 v0, 6, v2
	v_readlane_b32 s0, v243, 24
	s_nop 1
	v_add_u32_e32 v136, s0, v0
	s_movk_i32 s0, 0x4400
	v_cmp_gt_i32_e32 vcc, s0, v136
	s_and_saveexec_b64 s[8:9], vcc
	s_cbranch_execz .LBB0_68
	v_and_b32_e32 v4, 63, v2
	v_readlane_b32 s0, v243, 19
	v_readlane_b32 s1, v243, 20
	v_readlane_b32 s34, v240, 23
	v_readlane_b32 s10, v243, 52
	v_readlane_b32 s11, v243, 53
	v_lshlrev_b32_e32 v0, 3, v4
	v_mov_b32_e32 v1, v137
	v_lshlrev_b32_e32 v2, 4, v4
	v_mov_b32_e32 v3, v137
	s_cmp_eq_u32 s34, 6
	s_cselect_b32 s0, s0, s10
	s_cselect_b32 s1, s1, s11
	v_lshl_add_u64 v[0:1], s[96:97], 0, v[0:1]
	v_cmp_eq_u32_e32 vcc, 0, v4
	v_lshl_add_u64 v[2:3], s[0:1], 0, v[2:3]
	s_mov_b64 s[10:11], 0
	s_branch .LBB0_65

.LBB0_65:
	v_cmp_lt_i32_e64 s[0:1], s77, v136
	s_and_saveexec_b64 s[12:13], s[0:1]
	s_cbranch_execz .LBB0_64
	v_add_u32_e32 v6, 0xffffc000, v136
	s_waitcnt lgkmcnt(0)
	v_mov_b32_e32 v7, v137
	v_lshlrev_b64 v[6:7], 12, v[6:7]
	v_lshlrev_b64 v[4:5], 11, v[136:137]
	v_lshl_add_u64 v[24:25], v[2:3], 0, v[6:7]
	v_lshl_add_u64 v[4:5], v[0:1], 0, v[4:5]
	s_mov_b32 s34, 0x400000
	v_lshl_add_u64 v[26:27], v[24:25], 0, s[34:35]
	v_lshl_add_u64 v[28:29], v[26:27], 0, s[34:35]
	v_lshl_add_u64 v[30:31], v[28:29], 0, s[34:35]
	global_load_dwordx2 v[22:23], v[4:5], off
	global_load_dwordx2 v[32:33], v[4:5], off offset:512
	global_load_dwordx2 v[34:35], v[4:5], off offset:1024
	global_load_dwordx2 v[36:37], v[4:5], off offset:1536
	v_readlane_b32 s34, v240, 23
	s_cmp_eq_u32 s34, 6
	s_cbranch_scc1 .Lfin_four
	s_mov_b32 s34, 0x400000
	v_lshl_add_u64 v[198:199], v[30:31], 0, s[34:35]
	v_lshl_add_u64 v[200:201], v[198:199], 0, s[34:35]
	v_lshl_add_u64 v[202:203], v[200:201], 0, s[34:35]
	v_lshl_add_u64 v[204:205], v[202:203], 0, s[34:35]
	global_load_dwordx4 v[40:43], v[24:25], off
	global_load_dwordx4 v[44:47], v[26:27], off
	global_load_dwordx4 v[48:51], v[28:29], off
	global_load_dwordx4 v[52:55], v[30:31], off
	global_load_dwordx4 v[56:59], v[198:199], off
	global_load_dwordx4 v[60:63], v[200:201], off
	global_load_dwordx4 v[64:67], v[202:203], off
	global_load_dwordx4 v[68:71], v[204:205], off
	global_load_dwordx4 v[72:75], v[24:25], off offset:1024
	global_load_dwordx4 v[76:79], v[26:27], off offset:1024
	global_load_dwordx4 v[80:83], v[28:29], off offset:1024
	global_load_dwordx4 v[84:87], v[30:31], off offset:1024
	global_load_dwordx4 v[88:91], v[198:199], off offset:1024
	global_load_dwordx4 v[92:95], v[200:201], off offset:1024
	global_load_dwordx4 v[96:99], v[202:203], off offset:1024
	global_load_dwordx4 v[100:103], v[204:205], off offset:1024
	global_load_dwordx4 v[104:107], v[24:25], off offset:2048
	global_load_dwordx4 v[108:111], v[26:27], off offset:2048
	global_load_dwordx4 v[112:115], v[28:29], off offset:2048
	global_load_dwordx4 v[116:119], v[30:31], off offset:2048
	global_load_dwordx4 v[120:123], v[198:199], off offset:2048
	global_load_dwordx4 v[124:127], v[200:201], off offset:2048
	global_load_dwordx4 v[128:131], v[202:203], off offset:2048
	global_load_dwordx4 v[132:135], v[204:205], off offset:2048
	global_load_dwordx4 v[166:169], v[24:25], off offset:3072
	global_load_dwordx4 v[170:173], v[26:27], off offset:3072
	global_load_dwordx4 v[174:177], v[28:29], off offset:3072
	global_load_dwordx4 v[178:181], v[30:31], off offset:3072
	global_load_dwordx4 v[182:185], v[198:199], off offset:3072
	global_load_dwordx4 v[186:189], v[200:201], off offset:3072
	global_load_dwordx4 v[190:193], v[202:203], off offset:3072
	global_load_dwordx4 v[194:197], v[204:205], off offset:3072
	s_waitcnt vmcnt(24)
	v_lshlrev_b32_e32 v8, 16, v22
	v_and_b32_e32 v9, 0xffff0000, v22
	v_lshlrev_b32_e32 v10, 16, v23
	v_and_b32_e32 v11, 0xffff0000, v23
	v_pk_add_f32 v[8:9], v[40:41], v[8:9]
	v_pk_add_f32 v[10:11], v[42:43], v[10:11]
	v_pk_add_f32 v[8:9], v[44:45], v[8:9]
	v_pk_add_f32 v[10:11], v[46:47], v[10:11]
	v_pk_add_f32 v[8:9], v[48:49], v[8:9]
	v_pk_add_f32 v[10:11], v[50:51], v[10:11]
	v_pk_add_f32 v[8:9], v[52:53], v[8:9]
	v_pk_add_f32 v[10:11], v[54:55], v[10:11]
	v_pk_add_f32 v[8:9], v[56:57], v[8:9]
	v_pk_add_f32 v[10:11], v[58:59], v[10:11]
	v_pk_add_f32 v[8:9], v[60:61], v[8:9]
	v_pk_add_f32 v[10:11], v[62:63], v[10:11]
	v_pk_add_f32 v[8:9], v[64:65], v[8:9]
	v_pk_add_f32 v[10:11], v[66:67], v[10:11]
	v_pk_add_f32 v[8:9], v[68:69], v[8:9]
	v_pk_add_f32 v[10:11], v[70:71], v[10:11]
	v_mul_f32_e32 v6, v8, v8
	v_fmac_f32_e32 v6, v9, v9
	v_fmac_f32_e32 v6, v10, v10
	v_fmac_f32_e32 v6, v11, v11
	v_cvt_pk_bf16_f32 v14, v8, v9
	v_cvt_pk_bf16_f32 v15, v10, v11
	global_store_dwordx2 v[4:5], v[14:15], off
	s_waitcnt vmcnt(17)
	v_lshlrev_b32_e32 v8, 16, v32
	v_and_b32_e32 v9, 0xffff0000, v32
	v_lshlrev_b32_e32 v10, 16, v33
	v_and_b32_e32 v11, 0xffff0000, v33
	v_pk_add_f32 v[8:9], v[72:73], v[8:9]
	v_pk_add_f32 v[10:11], v[74:75], v[10:11]
	v_pk_add_f32 v[8:9], v[76:77], v[8:9]
	v_pk_add_f32 v[10:11], v[78:79], v[10:11]
	v_pk_add_f32 v[8:9], v[80:81], v[8:9]
	v_pk_add_f32 v[10:11], v[82:83], v[10:11]
	v_pk_add_f32 v[8:9], v[84:85], v[8:9]
	v_pk_add_f32 v[10:11], v[86:87], v[10:11]
	v_pk_add_f32 v[8:9], v[88:89], v[8:9]
	v_pk_add_f32 v[10:11], v[90:91], v[10:11]
	v_pk_add_f32 v[8:9], v[92:93], v[8:9]
	v_pk_add_f32 v[10:11], v[94:95], v[10:11]
	v_pk_add_f32 v[8:9], v[96:97], v[8:9]
	v_pk_add_f32 v[10:11], v[98:99], v[10:11]
	v_pk_add_f32 v[8:9], v[100:101], v[8:9]
	v_pk_add_f32 v[10:11], v[102:103], v[10:11]
	v_fmac_f32_e32 v6, v8, v8
	v_fmac_f32_e32 v6, v9, v9
	v_fmac_f32_e32 v6, v10, v10
	v_fmac_f32_e32 v6, v11, v11
	v_cvt_pk_bf16_f32 v16, v8, v9
	v_cvt_pk_bf16_f32 v17, v10, v11
	global_store_dwordx2 v[4:5], v[16:17], off offset:512
	s_waitcnt vmcnt(10)
	v_lshlrev_b32_e32 v8, 16, v34
	v_and_b32_e32 v9, 0xffff0000, v34
	v_lshlrev_b32_e32 v10, 16, v35
	v_and_b32_e32 v11, 0xffff0000, v35
	v_pk_add_f32 v[8:9], v[104:105], v[8:9]
	v_pk_add_f32 v[10:11], v[106:107], v[10:11]
	v_pk_add_f32 v[8:9], v[108:109], v[8:9]
	v_pk_add_f32 v[10:11], v[110:111], v[10:11]
	v_pk_add_f32 v[8:9], v[112:113], v[8:9]
	v_pk_add_f32 v[10:11], v[114:115], v[10:11]
	v_pk_add_f32 v[8:9], v[116:117], v[8:9]
	v_pk_add_f32 v[10:11], v[118:119], v[10:11]
	v_pk_add_f32 v[8:9], v[120:121], v[8:9]
	v_pk_add_f32 v[10:11], v[122:123], v[10:11]
	v_pk_add_f32 v[8:9], v[124:125], v[8:9]
	v_pk_add_f32 v[10:11], v[126:127], v[10:11]
	v_pk_add_f32 v[8:9], v[128:129], v[8:9]
	v_pk_add_f32 v[10:11], v[130:131], v[10:11]
	v_pk_add_f32 v[8:9], v[132:133], v[8:9]
	v_pk_add_f32 v[10:11], v[134:135], v[10:11]
	v_fmac_f32_e32 v6, v8, v8
	v_fmac_f32_e32 v6, v9, v9
	v_fmac_f32_e32 v6, v10, v10
	v_fmac_f32_e32 v6, v11, v11
	v_cvt_pk_bf16_f32 v18, v8, v9
	v_cvt_pk_bf16_f32 v19, v10, v11
	global_store_dwordx2 v[4:5], v[18:19], off offset:1024
	s_waitcnt vmcnt(3)
	v_lshlrev_b32_e32 v8, 16, v36
	v_and_b32_e32 v9, 0xffff0000, v36
	v_lshlrev_b32_e32 v10, 16, v37
	v_and_b32_e32 v11, 0xffff0000, v37
	v_pk_add_f32 v[8:9], v[166:167], v[8:9]
	v_pk_add_f32 v[10:11], v[168:169], v[10:11]
	v_pk_add_f32 v[8:9], v[170:171], v[8:9]
	v_pk_add_f32 v[10:11], v[172:173], v[10:11]
	v_pk_add_f32 v[8:9], v[174:175], v[8:9]
	v_pk_add_f32 v[10:11], v[176:177], v[10:11]
	v_pk_add_f32 v[8:9], v[178:179], v[8:9]
	v_pk_add_f32 v[10:11], v[180:181], v[10:11]
	v_pk_add_f32 v[8:9], v[182:183], v[8:9]
	v_pk_add_f32 v[10:11], v[184:185], v[10:11]
	v_pk_add_f32 v[8:9], v[186:187], v[8:9]
	v_pk_add_f32 v[10:11], v[188:189], v[10:11]
	v_pk_add_f32 v[8:9], v[190:191], v[8:9]
	v_pk_add_f32 v[10:11], v[192:193], v[10:11]
	v_pk_add_f32 v[8:9], v[194:195], v[8:9]
	v_pk_add_f32 v[10:11], v[196:197], v[10:11]
	v_fmac_f32_e32 v6, v8, v8
	v_fmac_f32_e32 v6, v9, v9
	v_fmac_f32_e32 v6, v10, v10
	v_fmac_f32_e32 v6, v11, v11
	v_cvt_pk_bf16_f32 v20, v8, v9
	v_cvt_pk_bf16_f32 v21, v10, v11
	global_store_dwordx2 v[4:5], v[20:21], off offset:1536
	s_branch .Lfin_reduce
.Lfin_four:
	global_load_dwordx4 v[40:43], v[24:25], off
	global_load_dwordx4 v[44:47], v[26:27], off
	global_load_dwordx4 v[48:51], v[28:29], off
	global_load_dwordx4 v[52:55], v[30:31], off
	global_load_dwordx4 v[56:59], v[24:25], off offset:1024
	global_load_dwordx4 v[60:63], v[26:27], off offset:1024
	global_load_dwordx4 v[64:67], v[28:29], off offset:1024
	global_load_dwordx4 v[68:71], v[30:31], off offset:1024
	global_load_dwordx4 v[72:75], v[24:25], off offset:2048
	global_load_dwordx4 v[76:79], v[26:27], off offset:2048
	global_load_dwordx4 v[80:83], v[28:29], off offset:2048
	global_load_dwordx4 v[84:87], v[30:31], off offset:2048
	global_load_dwordx4 v[88:91], v[24:25], off offset:3072
	global_load_dwordx4 v[92:95], v[26:27], off offset:3072
	global_load_dwordx4 v[96:99], v[28:29], off offset:3072
	global_load_dwordx4 v[100:103], v[30:31], off offset:3072
	s_waitcnt vmcnt(12)
	v_lshlrev_b32_e32 v8, 16, v22
	v_and_b32_e32 v9, 0xffff0000, v22
	v_lshlrev_b32_e32 v10, 16, v23
	v_and_b32_e32 v11, 0xffff0000, v23
	v_pk_add_f32 v[8:9], v[40:41], v[8:9]
	v_pk_add_f32 v[10:11], v[42:43], v[10:11]
	v_pk_add_f32 v[8:9], v[44:45], v[8:9]
	v_pk_add_f32 v[10:11], v[46:47], v[10:11]
	v_pk_add_f32 v[8:9], v[48:49], v[8:9]
	v_pk_add_f32 v[10:11], v[50:51], v[10:11]
	v_pk_add_f32 v[8:9], v[52:53], v[8:9]
	v_pk_add_f32 v[10:11], v[54:55], v[10:11]
	v_mul_f32_e32 v6, v8, v8
	v_fmac_f32_e32 v6, v9, v9
	v_fmac_f32_e32 v6, v10, v10
	v_fmac_f32_e32 v6, v11, v11
	v_cvt_pk_bf16_f32 v14, v8, v9
	v_cvt_pk_bf16_f32 v15, v10, v11
	global_store_dwordx2 v[4:5], v[14:15], off
	s_waitcnt vmcnt(9)
	v_lshlrev_b32_e32 v8, 16, v32
	v_and_b32_e32 v9, 0xffff0000, v32
	v_lshlrev_b32_e32 v10, 16, v33
	v_and_b32_e32 v11, 0xffff0000, v33
	v_pk_add_f32 v[8:9], v[56:57], v[8:9]
	v_pk_add_f32 v[10:11], v[58:59], v[10:11]
	v_pk_add_f32 v[8:9], v[60:61], v[8:9]
	v_pk_add_f32 v[10:11], v[62:63], v[10:11]
	v_pk_add_f32 v[8:9], v[64:65], v[8:9]
	v_pk_add_f32 v[10:11], v[66:67], v[10:11]
	v_pk_add_f32 v[8:9], v[68:69], v[8:9]
	v_pk_add_f32 v[10:11], v[70:71], v[10:11]
	v_fmac_f32_e32 v6, v8, v8
	v_fmac_f32_e32 v6, v9, v9
	v_fmac_f32_e32 v6, v10, v10
	v_fmac_f32_e32 v6, v11, v11
	v_cvt_pk_bf16_f32 v16, v8, v9
	v_cvt_pk_bf16_f32 v17, v10, v11
	global_store_dwordx2 v[4:5], v[16:17], off offset:512
	s_waitcnt vmcnt(6)
	v_lshlrev_b32_e32 v8, 16, v34
	v_and_b32_e32 v9, 0xffff0000, v34
	v_lshlrev_b32_e32 v10, 16, v35
	v_and_b32_e32 v11, 0xffff0000, v35
	v_pk_add_f32 v[8:9], v[72:73], v[8:9]
	v_pk_add_f32 v[10:11], v[74:75], v[10:11]
	v_pk_add_f32 v[8:9], v[76:77], v[8:9]
	v_pk_add_f32 v[10:11], v[78:79], v[10:11]
	v_pk_add_f32 v[8:9], v[80:81], v[8:9]
	v_pk_add_f32 v[10:11], v[82:83], v[10:11]
	v_pk_add_f32 v[8:9], v[84:85], v[8:9]
	v_pk_add_f32 v[10:11], v[86:87], v[10:11]
	v_fmac_f32_e32 v6, v8, v8
	v_fmac_f32_e32 v6, v9, v9
	v_fmac_f32_e32 v6, v10, v10
	v_fmac_f32_e32 v6, v11, v11
	v_cvt_pk_bf16_f32 v18, v8, v9
	v_cvt_pk_bf16_f32 v19, v10, v11
	global_store_dwordx2 v[4:5], v[18:19], off offset:1024
	s_waitcnt vmcnt(3)
	v_lshlrev_b32_e32 v8, 16, v36
	v_and_b32_e32 v9, 0xffff0000, v36
	v_lshlrev_b32_e32 v10, 16, v37
	v_and_b32_e32 v11, 0xffff0000, v37
	v_pk_add_f32 v[8:9], v[88:89], v[8:9]
	v_pk_add_f32 v[10:11], v[90:91], v[10:11]
	v_pk_add_f32 v[8:9], v[92:93], v[8:9]
	v_pk_add_f32 v[10:11], v[94:95], v[10:11]
	v_pk_add_f32 v[8:9], v[96:97], v[8:9]
	v_pk_add_f32 v[10:11], v[98:99], v[10:11]
	v_pk_add_f32 v[8:9], v[100:101], v[8:9]
	v_pk_add_f32 v[10:11], v[102:103], v[10:11]
	v_fmac_f32_e32 v6, v8, v8
	v_fmac_f32_e32 v6, v9, v9
	v_fmac_f32_e32 v6, v10, v10
	v_fmac_f32_e32 v6, v11, v11
	v_cvt_pk_bf16_f32 v20, v8, v9
	v_cvt_pk_bf16_f32 v21, v10, v11
	global_store_dwordx2 v[4:5], v[20:21], off offset:1536
.Lfin_reduce:
	v_xor_b32_e32 v12, 32, v164
	v_lshlrev_b32_e32 v12, 2, v12
	ds_bpermute_b32 v7, v12, v6
	s_waitcnt lgkmcnt(0)
	v_add_f32_e32 v6, v6, v7
	v_xor_b32_e32 v12, 16, v164
	v_lshlrev_b32_e32 v12, 2, v12
	ds_bpermute_b32 v7, v12, v6
	s_waitcnt lgkmcnt(0)
	v_add_f32_e32 v6, v6, v7
	v_xor_b32_e32 v12, 8, v164
	v_lshlrev_b32_e32 v12, 2, v12
	ds_bpermute_b32 v7, v12, v6
	s_waitcnt lgkmcnt(0)
	v_add_f32_e32 v6, v6, v7
	v_xor_b32_e32 v12, 4, v164
	v_lshlrev_b32_e32 v12, 2, v12
	ds_bpermute_b32 v7, v12, v6
	s_waitcnt lgkmcnt(0)
	v_add_f32_e32 v6, v6, v7
	v_xor_b32_e32 v12, 2, v164
	v_lshlrev_b32_e32 v12, 2, v12
	ds_bpermute_b32 v7, v12, v6
	s_waitcnt lgkmcnt(0)
	v_add_f32_e32 v6, v6, v7
	v_xor_b32_e32 v12, 1, v164
	v_lshlrev_b32_e32 v12, 2, v12
	ds_bpermute_b32 v7, v12, v6
	s_waitcnt lgkmcnt(0)
	s_and_b64 exec, exec, vcc
	s_cbranch_execz .LBB0_64
	v_lshl_add_u64 v[4:5], v[136:137], 2, s[6:7]
	s_waitcnt lgkmcnt(0)
	v_add_f32_e32 v6, v6, v7
	global_store_dword v[4:5], v6, off
	s_branch .LBB0_64

.LBB0_100:
	v_readlane_b32 s10, v243, 52
	v_readlane_b32 s38, v243, 26
	v_readlane_b32 s18, v240, 53
	v_readlane_b32 s16, v243, 21
	s_mov_b64 s[12:13], -1
	s_mov_b32 s48, 0.5
	s_movk_i32 s34, 0xb00
	s_movk_i32 s47, 0x400
	s_mov_b64 s[8:9], 0
	s_mov_b32 s44, 8
	s_mov_b32 s23, 1
	s_mov_b64 s[6:7], 0
	v_readlane_b32 s11, v243, 53
	s_mov_b64 s[14:15], s[96:97]
	v_readlane_b32 s39, v243, 27
	v_readlane_b32 s19, v240, 54
	v_readlane_b32 s17, v243, 22

.LBB0_372:
	s_andn2_b64 vcc, exec, s[0:1]
	s_cbranch_vccnz .LBB0_445
	v_readlane_b32 s0, v240, 23
	v_readlane_b32 s1, v243, 0
	s_cmp_eq_u32 s0, 5
	s_cbranch_scc0 .Lwd_not5
	s_cmp_lt_u32 s1, 64
	s_cbranch_scc1 .LBB0_445
	s_branch .Lwd_go
.Lwd_not5:
	s_cmp_eq_u32 s0, 8
	s_cbranch_scc1 .Lwd_go
	s_cmp_lt_u32 s1, 0x80
	s_cbranch_scc1 .LBB0_445
.Lwd_go:
	v_readlane_b32 s2, v240, 23
	s_mul_i32 s7, s24, 0x8c0
	s_mov_b64 s[4:5], -1
	s_mov_b64 s[0:1], 0
	s_cmp_lt_i32 s2, 5
	s_mov_b64 s[2:3], 0
	s_cbranch_scc0 .LBB0_695
	s_andn2_b64 vcc, exec, s[4:5]
	s_cbranch_vccz .LBB0_696

.LBB0_379:
	v_readlane_b32 s0, v240, 23
	v_readlane_b32 s1, v243, 0
	s_cmp_eq_u32 s0, 5
	s_cbranch_scc1 .Lwd_s5
	s_cmp_eq_u32 s0, 8
	s_cbranch_scc1 .Lwd_s8
	s_sub_i32 s0, s1, 0x80
	s_movk_i32 s1, 0x80
	s_branch .Lwd_set
.Lwd_s8:
	s_add_i32 s2, s6, 0x340
	s_cmp_lt_u32 s1, 0x80
	s_cbranch_scc1 .Lwd_s8low
	s_min_i32 s17, s17, s2
	s_sub_i32 s0, s1, 0x80
	s_movk_i32 s1, 0x80
	s_branch .Lwd_set
.Lwd_s8low:
	s_mov_b32 s6, s2
	s_mov_b32 s18, s16
	s_mov_b32 s0, s1
	s_movk_i32 s1, 0x80
	s_branch .Lwd_set
.Lwd_s5:
	s_sub_i32 s0, s1, 64
	s_movk_i32 s1, 0xc0
.Lwd_set:
	v_writelane_b32 v244, s0, 0
	v_writelane_b32 v244, s1, 1
	s_add_i32 s19, s6, s0
	s_branch .LBB0_381
.LBB0_380:
	v_readlane_b32 s0, v244, 1
	v_readlane_b32 s1, v242, 9
	s_nop 0
	s_add_i32 s19, s19, s0

.LBB0_444:
	v_readlane_b32 s0, v244, 0
	s_add_i32 s17, s18, s0
	s_cmp_ge_i32 s17, s16
	v_readlane_b32 s1, v242, 5
	s_cbranch_scc0 .LBB0_562

.LBB0_561:
	v_readlane_b32 s0, v244, 1
	v_readlane_b32 s1, v242, 9
	s_nop 0
	s_add_i32 s17, s17, s0
	s_cmp_lt_i32 s17, s16
	s_cbranch_scc0 .LBB0_445

	.amdhsa_kernel _Z4mega6Params
		.amdhsa_group_segment_fixed_size 0
		.amdhsa_private_segment_fixed_size 0
		.amdhsa_kernarg_size 512
		.amdhsa_user_sgpr_count 2
		.amdhsa_user_sgpr_dispatch_ptr 0
		.amdhsa_user_sgpr_queue_ptr 0
		.amdhsa_user_sgpr_kernarg_segment_ptr 1
		.amdhsa_user_sgpr_dispatch_id 0
		.amdhsa_user_sgpr_kernarg_preload_length 0
		.amdhsa_user_sgpr_kernarg_preload_offset 0
		.amdhsa_user_sgpr_private_segment_size 0
		.amdhsa_uses_dynamic_stack 0
		.amdhsa_enable_private_segment 0
		.amdhsa_system_sgpr_workgroup_id_x 1
		.amdhsa_system_sgpr_workgroup_id_y 0
		.amdhsa_system_sgpr_workgroup_id_z 0
		.amdhsa_system_sgpr_workgroup_info 0
		.amdhsa_system_vgpr_workitem_id 2
		.amdhsa_next_free_vgpr 248
		.amdhsa_next_free_sgpr 100
		.amdhsa_accum_offset 248
		.amdhsa_reserve_vcc 1
		.amdhsa_float_round_mode_32 0
		.amdhsa_float_round_mode_16_64 0
		.amdhsa_float_denorm_mode_32 3
		.amdhsa_float_denorm_mode_16_64 3
		.amdhsa_dx10_clamp 1
		.amdhsa_ieee_mode 1
		.amdhsa_fp16_overflow 0
		.amdhsa_tg_split 0
		.amdhsa_exception_fp_ieee_invalid_op 0
		.amdhsa_exception_fp_denorm_src 0
		.amdhsa_exception_fp_ieee_div_zero 0
		.amdhsa_exception_fp_ieee_overflow 0
		.amdhsa_exception_fp_ieee_underflow 0
		.amdhsa_exception_fp_ieee_inexact 0
		.amdhsa_exception_int_div_zero 0
	.end_amdhsa_kernel

.Lfunc_end0:
	.size	_Z4mega6Params, .Lfunc_end0-_Z4mega6Params
	.set _Z4mega6Params.num_vgpr, 248
	.set _Z4mega6Params.num_agpr, 0
	.set _Z4mega6Params.numbered_sgpr, 100
	.set _Z4mega6Params.num_named_barrier, 0
	.set _Z4mega6Params.private_seg_size, 0
	.set _Z4mega6Params.uses_vcc, 1
	.set _Z4mega6Params.uses_flat_scratch, 0
	.set _Z4mega6Params.has_dyn_sized_stack, 0
	.set _Z4mega6Params.has_recursion, 0
	.set _Z4mega6Params.has_indirect_call, 0

amdhsa.kernels:
  - .agpr_count:     0
    .args:
      - .offset:         0
        .size:           256
        .value_kind:     by_value
      - .offset:         256
        .size:           4
        .value_kind:     hidden_block_count_x
      - .offset:         260
        .size:           4
        .value_kind:     hidden_block_count_y
      - .offset:         264
        .size:           4
        .value_kind:     hidden_block_count_z
      - .offset:         268
        .size:           2
        .value_kind:     hidden_group_size_x
      - .offset:         270
        .size:           2
        .value_kind:     hidden_group_size_y
      - .offset:         272
        .size:           2
        .value_kind:     hidden_group_size_z
      - .offset:         274
        .size:           2
        .value_kind:     hidden_remainder_x
      - .offset:         276
        .size:           2
        .value_kind:     hidden_remainder_y
      - .offset:         278
        .size:           2
        .value_kind:     hidden_remainder_z
      - .offset:         296
        .size:           8
        .value_kind:     hidden_global_offset_x
      - .offset:         304
        .size:           8
        .value_kind:     hidden_global_offset_y
      - .offset:         312
        .size:           8
        .value_kind:     hidden_global_offset_z
      - .offset:         320
        .size:           2
        .value_kind:     hidden_grid_dims
      - .offset:         344
        .size:           8
        .value_kind:     hidden_multigrid_sync_arg
      - .offset:         376
        .size:           4
        .value_kind:     hidden_dynamic_lds_size
    .group_segment_fixed_size: 0
    .kernarg_segment_align: 8
    .kernarg_segment_size: 512
    .language:       OpenCL C
    .language_version:
      - 2
      - 0
    .max_flat_workgroup_size: 512
    .name:           _Z4mega6Params
    .private_segment_fixed_size: 0
    .sgpr_count:     106
    .sgpr_spill_count: 274
    .symbol:         _Z4mega6Params.kd
    .uniform_work_group_size: 1
    .uses_dynamic_stack: false
    .vgpr_count:     248
    .vgpr_spill_count: 0
    .wavefront_size: 64
